# i1 + x-to-bf16 conversion loop unrolled 4x (8 loads in flight per lane)
# baseline (speedup 1.0000x reference)
; DI unsigned pk2(float lo, float hi) { f32x2 v = {lo, hi}; bf16x2v b = __builtin_convertvector(v, bf16x2v); return __builtin_bit_cast(unsigned, b); }
; DI int tid_l() { int t = threadIdx.x; asm volatile("" : "+v"(t)); return t; }
; DI void phase0(const Params& p, char* lds) {
;     ...
;     bf16_t* ab = (bf16_t*)(ws + OFF_AB);
;     const size_t n8 = (size_t)NTOK * D / 8;
;     for (size_t i = (size_t)blockIdx.x * 512 + tid_l(); i < n8; i += (size_t)gridDim.x * 512) {
;       f32x4 a = *(const f32x4*)(((const float*)p.x_in) + i * 8), b = *(const f32x4*)(((const float*)p.x_in) + i * 8 + 4);
;       u32x4 o = {pk2(a[0], a[1]), pk2(a[2], a[3]), pk2(b[0], b[1]), pk2(b[2], b[3])};
;       *(u32x4*)(ab + i * 8) = o;
;     }
.LBB0_39:
	global_load_dwordx4 v[8:11], v[6:7], off offset:-16
	global_load_dwordx4 v[12:15], v[6:7], off
	v_lshl_add_u64 v[58:59], v[6:7], 0, s[12:13]
	global_load_dwordx4 v[60:63], v[58:59], off offset:-16
	global_load_dwordx4 v[64:67], v[58:59], off
	v_lshl_add_u64 v[58:59], v[58:59], 0, s[12:13]
	global_load_dwordx4 v[68:71], v[58:59], off offset:-16
	global_load_dwordx4 v[72:75], v[58:59], off
	v_lshl_add_u64 v[58:59], v[58:59], 0, s[12:13]
	global_load_dwordx4 v[76:79], v[58:59], off offset:-16
	global_load_dwordx4 v[80:83], v[58:59], off
	v_lshl_add_u64 v[6:7], v[58:59], 0, s[12:13]
	v_lshl_add_u64 v[2:3], v[2:3], 0, s[6:7]
	v_lshl_add_u64 v[2:3], v[2:3], 0, s[6:7]
	v_lshl_add_u64 v[2:3], v[2:3], 0, s[6:7]
	v_lshl_add_u64 v[2:3], v[2:3], 0, s[6:7]
	v_cmp_lt_u64_e32 vcc, s[16:17], v[2:3]
	s_or_b64 s[14:15], vcc, s[14:15]
	s_waitcnt vmcnt(7)
	v_cvt_pk_bf16_f32 v8, v8, v9
	v_cvt_pk_bf16_f32 v9, v10, v11
	s_waitcnt vmcnt(6)
	v_cvt_pk_bf16_f32 v10, v12, v13
	v_cvt_pk_bf16_f32 v11, v14, v15
	global_store_dwordx4 v[4:5], v[8:11], off
	v_lshl_add_u64 v[4:5], v[4:5], 0, s[8:9]
	s_waitcnt vmcnt(6)
	v_cvt_pk_bf16_f32 v60, v60, v61
	v_cvt_pk_bf16_f32 v61, v62, v63
	s_waitcnt vmcnt(5)
	v_cvt_pk_bf16_f32 v62, v64, v65
	v_cvt_pk_bf16_f32 v63, v66, v67
	global_store_dwordx4 v[4:5], v[60:63], off
	v_lshl_add_u64 v[4:5], v[4:5], 0, s[8:9]
	s_waitcnt vmcnt(5)
	v_cvt_pk_bf16_f32 v68, v68, v69
	v_cvt_pk_bf16_f32 v69, v70, v71
	s_waitcnt vmcnt(4)
	v_cvt_pk_bf16_f32 v70, v72, v73
	v_cvt_pk_bf16_f32 v71, v74, v75
	global_store_dwordx4 v[4:5], v[68:71], off
	v_lshl_add_u64 v[4:5], v[4:5], 0, s[8:9]
	s_waitcnt vmcnt(4)
	v_cvt_pk_bf16_f32 v76, v76, v77
	v_cvt_pk_bf16_f32 v77, v78, v79
	s_waitcnt vmcnt(3)
	v_cvt_pk_bf16_f32 v78, v80, v81
	v_cvt_pk_bf16_f32 v79, v82, v83
	global_store_dwordx4 v[4:5], v[76:79], off
	v_lshl_add_u64 v[4:5], v[4:5], 0, s[8:9]
	s_andn2_b64 exec, exec, s[14:15]
	s_cbranch_execnz .LBB0_39
